# SwiGLU / W_in epilogue stores: lanes re-mapped (ds_bpermute) so each aligned lane quad writes 64 contiguous bytes of one row; global instead of flat stores there
# speedup vs baseline: 1.0216x; 1.0069x over previous
; __device__ __forceinline__ unsigned cvt_pk_bf16(float lo, float hi) { unsigned r; asm volatile("v_cvt_pk_bf16_f32 %0, %1, %2" : "=v"(r) : "v"(lo), "v"(hi)); return r; }
;     __device__ __forceinline__ void operator()(const f32x4 (&acc)[2][2][4][2], const Unit& u, int wr, int wc, int fr, int fq) const {
;         const int row0 = u.pm * BM + wr * 64 + fr; const bool isg = u.pn >= 30;
;         bf16_t* base = isg ? Gt : Z; const int ld = isg ? 3072 : 7680; const int col0 = (isg ? (u.pn - 30) : u.pn) * BM + wc * 32 + 8 * fq;
; #pragma unroll
;         for (int ai = 0; ai < 2; ++ai)
; #pragma unroll
;             for (int m = 0; m < 4; ++m)
; #pragma unroll
;                 for (int bj = 0; bj < 2; ++bj) {
;                     f32x4 v0 = acc[ai][bj][m][0], v1 = acc[ai][bj][m][1];
;                     if (isg) {
; #pragma unroll
;                         for (int j = 0; j < 4; ++j) { v0[j] = 1.f + __builtin_amdgcn_exp2f(v0[j] * -1.44269504088896341f); v1[j] = 1.f + __builtin_amdgcn_exp2f(v1[j] * -1.44269504088896341f); }
;                     }
;                     u32x4 w; w.x = cvt_pk_bf16(v0[0], v0[1]); w.y = cvt_pk_bf16(v0[2], v0[3]); w.z = cvt_pk_bf16(v1[0], v1[1]); w.w = cvt_pk_bf16(v1[2], v1[3]);
;                     *(u32x4*)(base + (size_t)(row0 + ai * HALF + m * 16) * ld + col0 + bj * HALF) = w;
;                 }
.LBB0_321:
	v_readlane_b32 s14, v253, 12
	v_and_b32_e32 v159, 3, v231
	s_mov_b32 s34, s25
	v_bfe_u32 v160, v231, 2, 2
	v_lshrrev_b32_e32 v248, 4, v231
	v_lshl_add_u32 v160, v160, 2, v248
	v_lshl_add_u32 v248, v159, 4, v160
	v_lshlrev_b32_e32 v248, 2, v248
	s_mov_b32 s55, s2
	v_mov_b32_e32 v130, s14
	ds_read_b128 v[130:133], v130
	s_waitcnt lgkmcnt(0)
	v_readfirstlane_b32 s14, v130
	s_cmp_lg_u32 s14, 0
	s_cbranch_scc0 .LBB0_359
	v_readlane_b32 s14, v253, 13
	s_cmp_gt_i32 s53, 29
	v_readfirstlane_b32 s15, v133
	v_mov_b32_e32 v130, s14
	ds_read_b64 v[130:131], v130
	v_readfirstlane_b32 s42, v132
	s_cselect_b64 s[46:47], -1, 0
	s_cmp_lt_i32 s53, 30
	v_mov_b32_e32 v149, v121
	s_waitcnt lgkmcnt(0)
	v_readfirstlane_b32 s43, v131
	v_readfirstlane_b32 s56, v130
	v_mov_b32_e32 v148, v120
	v_mov_b32_e32 v155, v119
	v_mov_b32_e32 v154, v118
	v_mov_b32_e32 v151, v129
	v_mov_b32_e32 v150, v128
	v_mov_b32_e32 v153, v127
	v_mov_b32_e32 v152, v126
	s_cbranch_scc1 .LBB0_324
	v_mul_f32_e32 v131, 0xbfb8aa3b, v118
	v_mul_f32_e32 v149, 0xbfb8aa3b, v120
	v_mul_f32_e32 v130, 0xbfb8aa3b, v126
	v_exp_f32_e32 v146, v131
	v_mul_f32_e32 v131, 0xbfb8aa3b, v127
	v_mul_f32_e32 v147, 0xbfb8aa3b, v119
	v_mul_f32_e32 v148, 0xbfb8aa3b, v128
	v_exp_f32_e32 v154, v149
	v_mul_f32_e32 v149, 0xbfb8aa3b, v129
	v_mul_f32_e32 v150, 0xbfb8aa3b, v121
	v_exp_f32_e32 v130, v130
	v_exp_f32_e32 v131, v131
	v_exp_f32_e32 v148, v148
	v_exp_f32_e32 v149, v149
	v_exp_f32_e32 v155, v150
	v_exp_f32_e32 v147, v147
	v_pk_add_f32 v[152:153], v[130:131], 1.0 op_sel_hi:[1,0]
	v_pk_add_f32 v[150:151], v[148:149], 1.0 op_sel_hi:[1,0]
	v_pk_add_f32 v[148:149], v[154:155], 1.0 op_sel_hi:[1,0]
	v_pk_add_f32 v[154:155], v[146:147], 1.0 op_sel_hi:[1,0]
.LBB0_324:
	s_lshl_b32 s14, s54, 8
	s_lshl_b32 s57, s55, 6
	s_add_i32 s57, s57, s14
	s_and_b64 s[58:59], s[46:47], exec
	s_movk_i32 s14, 0xc00
	s_cselect_b32 s15, s43, s15
	s_cselect_b32 s14, s14, 0x1e00
	s_cselect_b32 s42, s56, s42
	v_mov_b32_e32 v131, s15
	s_lshl_b32 s15, s53, 8
	s_add_i32 s56, s15, 0xffffe200
	v_mov_b32_e32 v130, s42
	s_and_b64 s[42:43], s[46:47], exec
	s_cselect_b32 s15, s56, s15
	s_lshl_b32 s42, s34, 5
	s_add_i32 s42, s42, s15
	v_lshl_add_u32 v146, v159, 3, s42
	v_add_u32_e32 v161, s57, v160
	v_ashrrev_i32_e32 v147, 31, v146
	v_lshl_add_u64 v[130:131], v[146:147], 1, v[130:131]
	v_mad_i64_i32 v[146:147], s[42:43], s14, v161, 0
	v_lshl_add_u64 v[146:147], v[146:147], 1, v[130:131]
	v_cvt_pk_bf16_f32 v152, v152, v153
	v_cvt_pk_bf16_f32 v153, v150, v151
	v_cvt_pk_bf16_f32 v154, v154, v155
	v_cvt_pk_bf16_f32 v155, v148, v149
	v_cndmask_b32_e64 v148, 0, 1, s[46:47]
	ds_bpermute_b32 v152, v248, v152
	ds_bpermute_b32 v153, v248, v153
	ds_bpermute_b32 v154, v248, v154
	ds_bpermute_b32 v155, v248, v155
	s_waitcnt lgkmcnt(0)
	global_store_dwordx4 v[146:147], v[152:155], off
	v_cmp_ne_u32_e64 s[42:43], 1, v148
	s_andn2_b64 vcc, exec, s[46:47]
	v_mov_b32_e32 v149, v117
	v_mov_b32_e32 v148, v116
	v_mov_b32_e32 v155, v115
	v_mov_b32_e32 v154, v114
	v_mov_b32_e32 v151, v125
	v_mov_b32_e32 v150, v124
	v_mov_b32_e32 v153, v123
	v_mov_b32_e32 v152, v122
	s_cbranch_vccnz .LBB0_326
	v_mul_f32_e32 v149, 0xbfb8aa3b, v114
	v_mul_f32_e32 v151, 0xbfb8aa3b, v116
	v_mul_f32_e32 v148, 0xbfb8aa3b, v122
	v_exp_f32_e32 v154, v149
	v_mul_f32_e32 v149, 0xbfb8aa3b, v123
	v_mul_f32_e32 v152, 0xbfb8aa3b, v115
	v_mul_f32_e32 v150, 0xbfb8aa3b, v124
	v_exp_f32_e32 v162, v151
	v_mul_f32_e32 v151, 0xbfb8aa3b, v125
	v_mul_f32_e32 v153, 0xbfb8aa3b, v117
	v_exp_f32_e32 v148, v148
	v_exp_f32_e32 v149, v149
	v_exp_f32_e32 v150, v150
	v_exp_f32_e32 v151, v151
	v_exp_f32_e32 v163, v153
	v_exp_f32_e32 v155, v152
	v_pk_add_f32 v[152:153], v[148:149], 1.0 op_sel_hi:[1,0]
	v_pk_add_f32 v[150:151], v[150:151], 1.0 op_sel_hi:[1,0]
	v_pk_add_f32 v[148:149], v[162:163], 1.0 op_sel_hi:[1,0]
	v_pk_add_f32 v[154:155], v[154:155], 1.0 op_sel_hi:[1,0]
.LBB0_326:
	v_cvt_pk_bf16_f32 v152, v152, v153
	v_cvt_pk_bf16_f32 v153, v150, v151
	s_nop 0
	v_cvt_pk_bf16_f32 v154, v154, v155
	v_cvt_pk_bf16_f32 v155, v148, v149
	ds_bpermute_b32 v152, v248, v152
	ds_bpermute_b32 v153, v248, v153
	ds_bpermute_b32 v154, v248, v154
	ds_bpermute_b32 v155, v248, v155
	s_waitcnt lgkmcnt(0)
	global_store_dwordx4 v[146:147], v[152:155], off offset:256
	s_and_b64 vcc, exec, s[42:43]
	v_mov_b32_e32 v149, v105
	v_mov_b32_e32 v148, v104
	v_mov_b32_e32 v155, v103
	v_mov_b32_e32 v154, v102
	v_mov_b32_e32 v151, v113
	v_mov_b32_e32 v150, v112
	v_mov_b32_e32 v153, v111
	v_mov_b32_e32 v152, v110
	s_cbranch_vccnz .LBB0_328
	v_mul_f32_e32 v147, 0xbfb8aa3b, v102
	v_mul_f32_e32 v149, 0xbfb8aa3b, v104
	v_mul_f32_e32 v146, 0xbfb8aa3b, v110
	v_exp_f32_e32 v154, v147
	v_mul_f32_e32 v147, 0xbfb8aa3b, v111
	v_mul_f32_e32 v150, 0xbfb8aa3b, v103
	v_mul_f32_e32 v148, 0xbfb8aa3b, v112
	v_exp_f32_e32 v162, v149
	v_mul_f32_e32 v149, 0xbfb8aa3b, v113
	v_mul_f32_e32 v151, 0xbfb8aa3b, v105
	v_exp_f32_e32 v146, v146
	v_exp_f32_e32 v147, v147
	v_exp_f32_e32 v148, v148
	v_exp_f32_e32 v149, v149
	v_exp_f32_e32 v163, v151
	v_exp_f32_e32 v155, v150
	v_pk_add_f32 v[152:153], v[146:147], 1.0 op_sel_hi:[1,0]
	v_pk_add_f32 v[150:151], v[148:149], 1.0 op_sel_hi:[1,0]
	v_pk_add_f32 v[148:149], v[162:163], 1.0 op_sel_hi:[1,0]
	v_pk_add_f32 v[154:155], v[154:155], 1.0 op_sel_hi:[1,0]
; __device__ __forceinline__ unsigned cvt_pk_bf16(float lo, float hi) { unsigned r; asm volatile("v_cvt_pk_bf16_f32 %0, %1, %2" : "=v"(r) : "v"(lo), "v"(hi)); return r; }
;     __device__ __forceinline__ void operator()(const f32x4 (&acc)[2][2][4][2], const Unit& u, int wr, int wc, int fr, int fq) const {
;     ...
;             for (int m = 0; m < 4; ++m)
; #pragma unroll
;                 for (int bj = 0; bj < 2; ++bj) {
;                     f32x4 v0 = acc[ai][bj][m][0], v1 = acc[ai][bj][m][1];
;                     if (isg) {
; #pragma unroll
;                         for (int j = 0; j < 4; ++j) { v0[j] = 1.f + __builtin_amdgcn_exp2f(v0[j] * -1.44269504088896341f); v1[j] = 1.f + __builtin_amdgcn_exp2f(v1[j] * -1.44269504088896341f); }
;                     }
;                     u32x4 w; w.x = cvt_pk_bf16(v0[0], v0[1]); w.y = cvt_pk_bf16(v0[2], v0[3]); w.z = cvt_pk_bf16(v1[0], v1[1]); w.w = cvt_pk_bf16(v1[2], v1[3]);
;                     *(u32x4*)(base + (size_t)(row0 + ai * HALF + m * 16) * ld + col0 + bj * HALF) = w;
;                 }
.LBB0_328:
	v_add_u32_e32 v146, 16, v161
	v_mad_i64_i32 v[146:147], s[46:47], s14, v146, 0
	v_lshl_add_u64 v[146:147], v[146:147], 1, v[130:131]
	v_cvt_pk_bf16_f32 v152, v152, v153
	v_cvt_pk_bf16_f32 v153, v150, v151
	v_cvt_pk_bf16_f32 v154, v154, v155
	v_cvt_pk_bf16_f32 v155, v148, v149
	ds_bpermute_b32 v152, v248, v152
	ds_bpermute_b32 v153, v248, v153
	ds_bpermute_b32 v154, v248, v154
	ds_bpermute_b32 v155, v248, v155
	s_waitcnt lgkmcnt(0)
	global_store_dwordx4 v[146:147], v[152:155], off
	s_and_b64 vcc, exec, s[42:43]
	v_mov_b32_e32 v149, v101
	v_mov_b32_e32 v148, v100
	v_mov_b32_e32 v155, v99
	v_mov_b32_e32 v154, v98
	v_mov_b32_e32 v151, v109
	v_mov_b32_e32 v150, v108
	v_mov_b32_e32 v153, v107
	v_mov_b32_e32 v152, v106
	s_cbranch_vccnz .LBB0_330
	v_mul_f32_e32 v149, 0xbfb8aa3b, v98
	v_mul_f32_e32 v151, 0xbfb8aa3b, v100
	v_mul_f32_e32 v148, 0xbfb8aa3b, v106
	v_exp_f32_e32 v154, v149
	v_mul_f32_e32 v149, 0xbfb8aa3b, v107
	v_mul_f32_e32 v152, 0xbfb8aa3b, v99
	v_mul_f32_e32 v150, 0xbfb8aa3b, v108
	v_exp_f32_e32 v162, v151
	v_mul_f32_e32 v151, 0xbfb8aa3b, v109
	v_mul_f32_e32 v153, 0xbfb8aa3b, v101
	v_exp_f32_e32 v148, v148
	v_exp_f32_e32 v149, v149
	v_exp_f32_e32 v150, v150
	v_exp_f32_e32 v151, v151
	v_exp_f32_e32 v163, v153
	v_exp_f32_e32 v155, v152
	v_pk_add_f32 v[152:153], v[148:149], 1.0 op_sel_hi:[1,0]
	v_pk_add_f32 v[150:151], v[150:151], 1.0 op_sel_hi:[1,0]
	v_pk_add_f32 v[148:149], v[162:163], 1.0 op_sel_hi:[1,0]
	v_pk_add_f32 v[154:155], v[154:155], 1.0 op_sel_hi:[1,0]
.LBB0_330:
	v_cvt_pk_bf16_f32 v152, v152, v153
	v_cvt_pk_bf16_f32 v153, v150, v151
	s_nop 0
	v_cvt_pk_bf16_f32 v154, v154, v155
	v_cvt_pk_bf16_f32 v155, v148, v149
	ds_bpermute_b32 v152, v248, v152
	ds_bpermute_b32 v153, v248, v153
	ds_bpermute_b32 v154, v248, v154
	ds_bpermute_b32 v155, v248, v155
	s_waitcnt lgkmcnt(0)
	global_store_dwordx4 v[146:147], v[152:155], off offset:256
	s_and_b64 vcc, exec, s[42:43]
	v_mov_b32_e32 v149, v89
	v_mov_b32_e32 v148, v88
	v_mov_b32_e32 v155, v87
	v_mov_b32_e32 v154, v86
	v_mov_b32_e32 v151, v97
	v_mov_b32_e32 v150, v96
	v_mov_b32_e32 v153, v95
	v_mov_b32_e32 v152, v94
	s_cbranch_vccnz .LBB0_332
	v_mul_f32_e32 v147, 0xbfb8aa3b, v86
	v_mul_f32_e32 v149, 0xbfb8aa3b, v88
	v_mul_f32_e32 v146, 0xbfb8aa3b, v94
	v_exp_f32_e32 v154, v147
	v_mul_f32_e32 v147, 0xbfb8aa3b, v95
	v_mul_f32_e32 v150, 0xbfb8aa3b, v87
	v_mul_f32_e32 v148, 0xbfb8aa3b, v96
	v_exp_f32_e32 v162, v149
	v_mul_f32_e32 v149, 0xbfb8aa3b, v97
	v_mul_f32_e32 v151, 0xbfb8aa3b, v89
	v_exp_f32_e32 v146, v146
	v_exp_f32_e32 v147, v147
	v_exp_f32_e32 v148, v148
	v_exp_f32_e32 v149, v149
	v_exp_f32_e32 v163, v151
	v_exp_f32_e32 v155, v150
	v_pk_add_f32 v[152:153], v[146:147], 1.0 op_sel_hi:[1,0]
	v_pk_add_f32 v[150:151], v[148:149], 1.0 op_sel_hi:[1,0]
	v_pk_add_f32 v[148:149], v[162:163], 1.0 op_sel_hi:[1,0]
	v_pk_add_f32 v[154:155], v[154:155], 1.0 op_sel_hi:[1,0]
.LBB0_332:
	v_add_u32_e32 v146, 32, v161
	v_mad_i64_i32 v[146:147], s[46:47], s14, v146, 0
	v_lshl_add_u64 v[146:147], v[146:147], 1, v[130:131]
	v_cvt_pk_bf16_f32 v152, v152, v153
	v_cvt_pk_bf16_f32 v153, v150, v151
	v_cvt_pk_bf16_f32 v154, v154, v155
	v_cvt_pk_bf16_f32 v155, v148, v149
	ds_bpermute_b32 v152, v248, v152
	ds_bpermute_b32 v153, v248, v153
	ds_bpermute_b32 v154, v248, v154
	ds_bpermute_b32 v155, v248, v155
	s_waitcnt lgkmcnt(0)
	global_store_dwordx4 v[146:147], v[152:155], off
	s_and_b64 vcc, exec, s[42:43]
	v_mov_b32_e32 v149, v85
	v_mov_b32_e32 v148, v84
	v_mov_b32_e32 v155, v83
	v_mov_b32_e32 v154, v82
	v_mov_b32_e32 v151, v93
	v_mov_b32_e32 v150, v92
	v_mov_b32_e32 v153, v91
	v_mov_b32_e32 v152, v90
	s_cbranch_vccnz .LBB0_334
	v_mul_f32_e32 v149, 0xbfb8aa3b, v82
	v_mul_f32_e32 v151, 0xbfb8aa3b, v84
	v_mul_f32_e32 v148, 0xbfb8aa3b, v90
	v_exp_f32_e32 v154, v149
	v_mul_f32_e32 v149, 0xbfb8aa3b, v91
	v_mul_f32_e32 v152, 0xbfb8aa3b, v83
	v_mul_f32_e32 v150, 0xbfb8aa3b, v92
	v_exp_f32_e32 v162, v151
	v_mul_f32_e32 v151, 0xbfb8aa3b, v93
	v_mul_f32_e32 v153, 0xbfb8aa3b, v85
	v_exp_f32_e32 v148, v148
	v_exp_f32_e32 v149, v149
	v_exp_f32_e32 v150, v150
	v_exp_f32_e32 v151, v151
	v_exp_f32_e32 v163, v153
	v_exp_f32_e32 v155, v152
	v_pk_add_f32 v[152:153], v[148:149], 1.0 op_sel_hi:[1,0]
	v_pk_add_f32 v[150:151], v[150:151], 1.0 op_sel_hi:[1,0]
	v_pk_add_f32 v[148:149], v[162:163], 1.0 op_sel_hi:[1,0]
	v_pk_add_f32 v[154:155], v[154:155], 1.0 op_sel_hi:[1,0]
.LBB0_334:
	v_cvt_pk_bf16_f32 v152, v152, v153
	v_cvt_pk_bf16_f32 v153, v150, v151
	s_nop 0
	v_cvt_pk_bf16_f32 v154, v154, v155
	v_cvt_pk_bf16_f32 v155, v148, v149
	ds_bpermute_b32 v152, v248, v152
	ds_bpermute_b32 v153, v248, v153
	ds_bpermute_b32 v154, v248, v154
	ds_bpermute_b32 v155, v248, v155
	s_waitcnt lgkmcnt(0)
	global_store_dwordx4 v[146:147], v[152:155], off offset:256
	s_and_b64 vcc, exec, s[42:43]
	v_mov_b32_e32 v149, v73
	v_mov_b32_e32 v148, v72
	v_mov_b32_e32 v155, v71
	v_mov_b32_e32 v154, v70
	v_mov_b32_e32 v151, v81
	v_mov_b32_e32 v150, v80
	v_mov_b32_e32 v153, v79
	v_mov_b32_e32 v152, v78
	s_cbranch_vccnz .LBB0_336
	v_mul_f32_e32 v147, 0xbfb8aa3b, v70
	v_mul_f32_e32 v149, 0xbfb8aa3b, v72
	v_mul_f32_e32 v146, 0xbfb8aa3b, v78
	v_exp_f32_e32 v154, v147
	v_mul_f32_e32 v147, 0xbfb8aa3b, v79
	v_mul_f32_e32 v150, 0xbfb8aa3b, v71
	v_mul_f32_e32 v148, 0xbfb8aa3b, v80
	v_exp_f32_e32 v162, v149
	v_mul_f32_e32 v149, 0xbfb8aa3b, v81
	v_mul_f32_e32 v151, 0xbfb8aa3b, v73
	v_exp_f32_e32 v146, v146
	v_exp_f32_e32 v147, v147
	v_exp_f32_e32 v148, v148
	v_exp_f32_e32 v149, v149
	v_exp_f32_e32 v163, v151
	v_exp_f32_e32 v155, v150
	v_pk_add_f32 v[152:153], v[146:147], 1.0 op_sel_hi:[1,0]
	v_pk_add_f32 v[150:151], v[148:149], 1.0 op_sel_hi:[1,0]
	v_pk_add_f32 v[148:149], v[162:163], 1.0 op_sel_hi:[1,0]
	v_pk_add_f32 v[154:155], v[154:155], 1.0 op_sel_hi:[1,0]
; __device__ __forceinline__ unsigned cvt_pk_bf16(float lo, float hi) { unsigned r; asm volatile("v_cvt_pk_bf16_f32 %0, %1, %2" : "=v"(r) : "v"(lo), "v"(hi)); return r; }
;     __device__ __forceinline__ void operator()(const f32x4 (&acc)[2][2][4][2], const Unit& u, int wr, int wc, int fr, int fq) const {
;     ...
;             for (int m = 0; m < 4; ++m)
; #pragma unroll
;                 for (int bj = 0; bj < 2; ++bj) {
;                     f32x4 v0 = acc[ai][bj][m][0], v1 = acc[ai][bj][m][1];
;                     if (isg) {
; #pragma unroll
;                         for (int j = 0; j < 4; ++j) { v0[j] = 1.f + __builtin_amdgcn_exp2f(v0[j] * -1.44269504088896341f); v1[j] = 1.f + __builtin_amdgcn_exp2f(v1[j] * -1.44269504088896341f); }
;                     }
;                     u32x4 w; w.x = cvt_pk_bf16(v0[0], v0[1]); w.y = cvt_pk_bf16(v0[2], v0[3]); w.z = cvt_pk_bf16(v1[0], v1[1]); w.w = cvt_pk_bf16(v1[2], v1[3]);
;                     *(u32x4*)(base + (size_t)(row0 + ai * HALF + m * 16) * ld + col0 + bj * HALF) = w;
;                 }
.LBB0_336:
	v_add_u32_e32 v146, 48, v161
	v_mad_i64_i32 v[146:147], s[46:47], s14, v146, 0
	v_lshl_add_u64 v[146:147], v[146:147], 1, v[130:131]
	v_cvt_pk_bf16_f32 v152, v152, v153
	v_cvt_pk_bf16_f32 v153, v150, v151
	v_cvt_pk_bf16_f32 v154, v154, v155
	v_cvt_pk_bf16_f32 v155, v148, v149
	ds_bpermute_b32 v152, v248, v152
	ds_bpermute_b32 v153, v248, v153
	ds_bpermute_b32 v154, v248, v154
	ds_bpermute_b32 v155, v248, v155
	s_waitcnt lgkmcnt(0)
	global_store_dwordx4 v[146:147], v[152:155], off
	s_and_b64 vcc, exec, s[42:43]
	v_mov_b32_e32 v149, v69
	v_mov_b32_e32 v148, v68
	v_mov_b32_e32 v155, v67
	v_mov_b32_e32 v154, v66
	v_mov_b32_e32 v151, v77
	v_mov_b32_e32 v150, v76
	v_mov_b32_e32 v153, v75
	v_mov_b32_e32 v152, v74
	s_cbranch_vccnz .LBB0_338
	v_mul_f32_e32 v149, 0xbfb8aa3b, v66
	v_mul_f32_e32 v151, 0xbfb8aa3b, v68
	v_mul_f32_e32 v148, 0xbfb8aa3b, v74
	v_exp_f32_e32 v154, v149
	v_mul_f32_e32 v149, 0xbfb8aa3b, v75
	v_mul_f32_e32 v152, 0xbfb8aa3b, v67
	v_mul_f32_e32 v150, 0xbfb8aa3b, v76
	v_exp_f32_e32 v162, v151
	v_mul_f32_e32 v151, 0xbfb8aa3b, v77
	v_mul_f32_e32 v153, 0xbfb8aa3b, v69
	v_exp_f32_e32 v148, v148
	v_exp_f32_e32 v149, v149
	v_exp_f32_e32 v150, v150
	v_exp_f32_e32 v151, v151
	v_exp_f32_e32 v163, v153
	v_exp_f32_e32 v155, v152
	v_pk_add_f32 v[152:153], v[148:149], 1.0 op_sel_hi:[1,0]
	v_pk_add_f32 v[150:151], v[150:151], 1.0 op_sel_hi:[1,0]
	v_pk_add_f32 v[148:149], v[162:163], 1.0 op_sel_hi:[1,0]
	v_pk_add_f32 v[154:155], v[154:155], 1.0 op_sel_hi:[1,0]
.LBB0_338:
	v_cvt_pk_bf16_f32 v152, v152, v153
	v_cvt_pk_bf16_f32 v153, v150, v151
	s_nop 0
	v_cvt_pk_bf16_f32 v154, v154, v155
	v_cvt_pk_bf16_f32 v155, v148, v149
	ds_bpermute_b32 v152, v248, v152
	ds_bpermute_b32 v153, v248, v153
	ds_bpermute_b32 v154, v248, v154
	ds_bpermute_b32 v155, v248, v155
	s_waitcnt lgkmcnt(0)
	global_store_dwordx4 v[146:147], v[152:155], off offset:256
	s_and_b64 vcc, exec, s[42:43]
	v_mov_b32_e32 v149, v57
	v_mov_b32_e32 v148, v56
	v_mov_b32_e32 v155, v55
	v_mov_b32_e32 v154, v54
	v_mov_b32_e32 v151, v65
	v_mov_b32_e32 v150, v64
	v_mov_b32_e32 v153, v63
	v_mov_b32_e32 v152, v62
	s_cbranch_vccnz .LBB0_340
	v_mul_f32_e32 v147, 0xbfb8aa3b, v54
	v_mul_f32_e32 v149, 0xbfb8aa3b, v56
	v_mul_f32_e32 v146, 0xbfb8aa3b, v62
	v_exp_f32_e32 v154, v147
	v_mul_f32_e32 v147, 0xbfb8aa3b, v63
	v_mul_f32_e32 v150, 0xbfb8aa3b, v55
	v_mul_f32_e32 v148, 0xbfb8aa3b, v64
	v_exp_f32_e32 v162, v149
	v_mul_f32_e32 v149, 0xbfb8aa3b, v65
	v_mul_f32_e32 v151, 0xbfb8aa3b, v57
	v_exp_f32_e32 v146, v146
	v_exp_f32_e32 v147, v147
	v_exp_f32_e32 v148, v148
	v_exp_f32_e32 v149, v149
	v_exp_f32_e32 v163, v151
	v_exp_f32_e32 v155, v150
	v_pk_add_f32 v[152:153], v[146:147], 1.0 op_sel_hi:[1,0]
	v_pk_add_f32 v[150:151], v[148:149], 1.0 op_sel_hi:[1,0]
	v_pk_add_f32 v[148:149], v[162:163], 1.0 op_sel_hi:[1,0]
	v_pk_add_f32 v[154:155], v[154:155], 1.0 op_sel_hi:[1,0]
.LBB0_340:
	v_add_u32_e32 v146, 0x80, v161
	v_mad_i64_i32 v[146:147], s[46:47], s14, v146, 0
	v_lshl_add_u64 v[146:147], v[146:147], 1, v[130:131]
	v_cvt_pk_bf16_f32 v152, v152, v153
	v_cvt_pk_bf16_f32 v153, v150, v151
	v_cvt_pk_bf16_f32 v154, v154, v155
	v_cvt_pk_bf16_f32 v155, v148, v149
	ds_bpermute_b32 v152, v248, v152
	ds_bpermute_b32 v153, v248, v153
	ds_bpermute_b32 v154, v248, v154
	ds_bpermute_b32 v155, v248, v155
	s_waitcnt lgkmcnt(0)
	global_store_dwordx4 v[146:147], v[152:155], off
	s_and_b64 vcc, exec, s[42:43]
	v_mov_b32_e32 v149, v53
	v_mov_b32_e32 v148, v52
	v_mov_b32_e32 v155, v51
	v_mov_b32_e32 v154, v50
	v_mov_b32_e32 v151, v61
	v_mov_b32_e32 v150, v60
	v_mov_b32_e32 v153, v59
	v_mov_b32_e32 v152, v58
	s_cbranch_vccnz .LBB0_342
	v_mul_f32_e32 v149, 0xbfb8aa3b, v50
	v_mul_f32_e32 v151, 0xbfb8aa3b, v52
	v_mul_f32_e32 v148, 0xbfb8aa3b, v58
	v_exp_f32_e32 v154, v149
	v_mul_f32_e32 v149, 0xbfb8aa3b, v59
	v_mul_f32_e32 v152, 0xbfb8aa3b, v51
	v_mul_f32_e32 v150, 0xbfb8aa3b, v60
	v_exp_f32_e32 v162, v151
	v_mul_f32_e32 v151, 0xbfb8aa3b, v61
	v_mul_f32_e32 v153, 0xbfb8aa3b, v53
	v_exp_f32_e32 v148, v148
	v_exp_f32_e32 v149, v149
	v_exp_f32_e32 v150, v150
	v_exp_f32_e32 v151, v151
	v_exp_f32_e32 v163, v153
	v_exp_f32_e32 v155, v152
	v_pk_add_f32 v[152:153], v[148:149], 1.0 op_sel_hi:[1,0]
	v_pk_add_f32 v[150:151], v[150:151], 1.0 op_sel_hi:[1,0]
	v_pk_add_f32 v[148:149], v[162:163], 1.0 op_sel_hi:[1,0]
	v_pk_add_f32 v[154:155], v[154:155], 1.0 op_sel_hi:[1,0]
.LBB0_342:
	v_cvt_pk_bf16_f32 v152, v152, v153
	v_cvt_pk_bf16_f32 v153, v150, v151
	s_nop 0
	v_cvt_pk_bf16_f32 v154, v154, v155
	v_cvt_pk_bf16_f32 v155, v148, v149
	ds_bpermute_b32 v152, v248, v152
	ds_bpermute_b32 v153, v248, v153
	ds_bpermute_b32 v154, v248, v154
	ds_bpermute_b32 v155, v248, v155
	s_waitcnt lgkmcnt(0)
	global_store_dwordx4 v[146:147], v[152:155], off offset:256
	s_and_b64 vcc, exec, s[42:43]
	v_mov_b32_e32 v149, v41
	v_mov_b32_e32 v148, v40
	v_mov_b32_e32 v155, v39
	v_mov_b32_e32 v154, v38
	v_mov_b32_e32 v151, v49
	v_mov_b32_e32 v150, v48
	v_mov_b32_e32 v153, v47
	v_mov_b32_e32 v152, v46
	s_cbranch_vccnz .LBB0_344
	v_mul_f32_e32 v147, 0xbfb8aa3b, v38
	v_mul_f32_e32 v149, 0xbfb8aa3b, v40
	v_mul_f32_e32 v146, 0xbfb8aa3b, v46
	v_exp_f32_e32 v154, v147
	v_mul_f32_e32 v147, 0xbfb8aa3b, v47
	v_mul_f32_e32 v150, 0xbfb8aa3b, v39
	v_mul_f32_e32 v148, 0xbfb8aa3b, v48
	v_exp_f32_e32 v162, v149
	v_mul_f32_e32 v149, 0xbfb8aa3b, v49
	v_mul_f32_e32 v151, 0xbfb8aa3b, v41
	v_exp_f32_e32 v146, v146
	v_exp_f32_e32 v147, v147
	v_exp_f32_e32 v148, v148
	v_exp_f32_e32 v149, v149
	v_exp_f32_e32 v163, v151
	v_exp_f32_e32 v155, v150
	v_pk_add_f32 v[152:153], v[146:147], 1.0 op_sel_hi:[1,0]
	v_pk_add_f32 v[150:151], v[148:149], 1.0 op_sel_hi:[1,0]
	v_pk_add_f32 v[148:149], v[162:163], 1.0 op_sel_hi:[1,0]
	v_pk_add_f32 v[154:155], v[154:155], 1.0 op_sel_hi:[1,0]
; __device__ __forceinline__ unsigned cvt_pk_bf16(float lo, float hi) { unsigned r; asm volatile("v_cvt_pk_bf16_f32 %0, %1, %2" : "=v"(r) : "v"(lo), "v"(hi)); return r; }
;     __device__ __forceinline__ void operator()(const f32x4 (&acc)[2][2][4][2], const Unit& u, int wr, int wc, int fr, int fq) const {
;     ...
;             for (int m = 0; m < 4; ++m)
; #pragma unroll
;                 for (int bj = 0; bj < 2; ++bj) {
;                     f32x4 v0 = acc[ai][bj][m][0], v1 = acc[ai][bj][m][1];
;                     if (isg) {
; #pragma unroll
;                         for (int j = 0; j < 4; ++j) { v0[j] = 1.f + __builtin_amdgcn_exp2f(v0[j] * -1.44269504088896341f); v1[j] = 1.f + __builtin_amdgcn_exp2f(v1[j] * -1.44269504088896341f); }
;                     }
;                     u32x4 w; w.x = cvt_pk_bf16(v0[0], v0[1]); w.y = cvt_pk_bf16(v0[2], v0[3]); w.z = cvt_pk_bf16(v1[0], v1[1]); w.w = cvt_pk_bf16(v1[2], v1[3]);
;                     *(u32x4*)(base + (size_t)(row0 + ai * HALF + m * 16) * ld + col0 + bj * HALF) = w;
;                 }
.LBB0_344:
	v_add_u32_e32 v146, 0x90, v161
	v_mad_i64_i32 v[146:147], s[46:47], s14, v146, 0
	v_lshl_add_u64 v[146:147], v[146:147], 1, v[130:131]
	v_cvt_pk_bf16_f32 v152, v152, v153
	v_cvt_pk_bf16_f32 v153, v150, v151
	v_cvt_pk_bf16_f32 v154, v154, v155
	v_cvt_pk_bf16_f32 v155, v148, v149
	ds_bpermute_b32 v152, v248, v152
	ds_bpermute_b32 v153, v248, v153
	ds_bpermute_b32 v154, v248, v154
	ds_bpermute_b32 v155, v248, v155
	s_waitcnt lgkmcnt(0)
	global_store_dwordx4 v[146:147], v[152:155], off
	s_and_b64 vcc, exec, s[42:43]
	v_mov_b32_e32 v149, v37
	v_mov_b32_e32 v148, v36
	v_mov_b32_e32 v155, v35
	v_mov_b32_e32 v154, v34
	v_mov_b32_e32 v151, v45
	v_mov_b32_e32 v150, v44
	v_mov_b32_e32 v153, v43
	v_mov_b32_e32 v152, v42
	s_cbranch_vccnz .LBB0_346
	v_mul_f32_e32 v149, 0xbfb8aa3b, v34
	v_mul_f32_e32 v151, 0xbfb8aa3b, v36
	v_mul_f32_e32 v148, 0xbfb8aa3b, v42
	v_exp_f32_e32 v154, v149
	v_mul_f32_e32 v149, 0xbfb8aa3b, v43
	v_mul_f32_e32 v152, 0xbfb8aa3b, v35
	v_mul_f32_e32 v150, 0xbfb8aa3b, v44
	v_exp_f32_e32 v162, v151
	v_mul_f32_e32 v151, 0xbfb8aa3b, v45
	v_mul_f32_e32 v153, 0xbfb8aa3b, v37
	v_exp_f32_e32 v148, v148
	v_exp_f32_e32 v149, v149
	v_exp_f32_e32 v150, v150
	v_exp_f32_e32 v151, v151
	v_exp_f32_e32 v163, v153
	v_exp_f32_e32 v155, v152
	v_pk_add_f32 v[152:153], v[148:149], 1.0 op_sel_hi:[1,0]
	v_pk_add_f32 v[150:151], v[150:151], 1.0 op_sel_hi:[1,0]
	v_pk_add_f32 v[148:149], v[162:163], 1.0 op_sel_hi:[1,0]
	v_pk_add_f32 v[154:155], v[154:155], 1.0 op_sel_hi:[1,0]
.LBB0_346:
	v_cvt_pk_bf16_f32 v152, v152, v153
	v_cvt_pk_bf16_f32 v153, v150, v151
	s_nop 0
	v_cvt_pk_bf16_f32 v154, v154, v155
	v_cvt_pk_bf16_f32 v155, v148, v149
	ds_bpermute_b32 v152, v248, v152
	ds_bpermute_b32 v153, v248, v153
	ds_bpermute_b32 v154, v248, v154
	ds_bpermute_b32 v155, v248, v155
	s_waitcnt lgkmcnt(0)
	global_store_dwordx4 v[146:147], v[152:155], off offset:256
	s_and_b64 vcc, exec, s[42:43]
	v_mov_b32_e32 v149, v25
	v_mov_b32_e32 v148, v24
	v_mov_b32_e32 v155, v23
	v_mov_b32_e32 v154, v22
	v_mov_b32_e32 v151, v33
	v_mov_b32_e32 v150, v32
	v_mov_b32_e32 v153, v31
	v_mov_b32_e32 v152, v30
	s_cbranch_vccnz .LBB0_348
	v_mul_f32_e32 v147, 0xbfb8aa3b, v22
	v_mul_f32_e32 v149, 0xbfb8aa3b, v24
	v_mul_f32_e32 v146, 0xbfb8aa3b, v30
	v_exp_f32_e32 v154, v147
	v_mul_f32_e32 v147, 0xbfb8aa3b, v31
	v_mul_f32_e32 v150, 0xbfb8aa3b, v23
	v_mul_f32_e32 v148, 0xbfb8aa3b, v32
	v_exp_f32_e32 v162, v149
	v_mul_f32_e32 v149, 0xbfb8aa3b, v33
	v_mul_f32_e32 v151, 0xbfb8aa3b, v25
	v_exp_f32_e32 v146, v146
	v_exp_f32_e32 v147, v147
	v_exp_f32_e32 v148, v148
	v_exp_f32_e32 v149, v149
	v_exp_f32_e32 v163, v151
	v_exp_f32_e32 v155, v150
	v_pk_add_f32 v[152:153], v[146:147], 1.0 op_sel_hi:[1,0]
	v_pk_add_f32 v[150:151], v[148:149], 1.0 op_sel_hi:[1,0]
	v_pk_add_f32 v[148:149], v[162:163], 1.0 op_sel_hi:[1,0]
	v_pk_add_f32 v[154:155], v[154:155], 1.0 op_sel_hi:[1,0]
.LBB0_348:
	v_add_u32_e32 v146, 0xa0, v161
	v_mad_i64_i32 v[146:147], s[46:47], s14, v146, 0
	v_lshl_add_u64 v[146:147], v[146:147], 1, v[130:131]
	v_cvt_pk_bf16_f32 v152, v152, v153
	v_cvt_pk_bf16_f32 v153, v150, v151
	v_cvt_pk_bf16_f32 v154, v154, v155
	v_cvt_pk_bf16_f32 v155, v148, v149
	ds_bpermute_b32 v152, v248, v152
	ds_bpermute_b32 v153, v248, v153
	ds_bpermute_b32 v154, v248, v154
	ds_bpermute_b32 v155, v248, v155
	s_waitcnt lgkmcnt(0)
	global_store_dwordx4 v[146:147], v[152:155], off
	s_and_b64 vcc, exec, s[42:43]
	v_mov_b32_e32 v149, v21
	v_mov_b32_e32 v148, v20
	v_mov_b32_e32 v155, v19
	v_mov_b32_e32 v154, v18
	v_mov_b32_e32 v151, v29
	v_mov_b32_e32 v150, v28
	v_mov_b32_e32 v153, v27
	v_mov_b32_e32 v152, v26
	s_cbranch_vccnz .LBB0_350
	v_mul_f32_e32 v149, 0xbfb8aa3b, v18
	v_mul_f32_e32 v151, 0xbfb8aa3b, v20
	v_mul_f32_e32 v148, 0xbfb8aa3b, v26
	v_exp_f32_e32 v154, v149
	v_mul_f32_e32 v149, 0xbfb8aa3b, v27
	v_mul_f32_e32 v152, 0xbfb8aa3b, v19
	v_mul_f32_e32 v150, 0xbfb8aa3b, v28
	v_exp_f32_e32 v162, v151
	v_mul_f32_e32 v151, 0xbfb8aa3b, v29
	v_mul_f32_e32 v153, 0xbfb8aa3b, v21
	v_exp_f32_e32 v148, v148
	v_exp_f32_e32 v149, v149
	v_exp_f32_e32 v150, v150
	v_exp_f32_e32 v151, v151
	v_exp_f32_e32 v163, v153
	v_exp_f32_e32 v155, v152
	v_pk_add_f32 v[152:153], v[148:149], 1.0 op_sel_hi:[1,0]
	v_pk_add_f32 v[150:151], v[150:151], 1.0 op_sel_hi:[1,0]
	v_pk_add_f32 v[148:149], v[162:163], 1.0 op_sel_hi:[1,0]
	v_pk_add_f32 v[154:155], v[154:155], 1.0 op_sel_hi:[1,0]
.LBB0_350:
	v_cvt_pk_bf16_f32 v152, v152, v153
	v_cvt_pk_bf16_f32 v153, v150, v151
	s_nop 0
	v_cvt_pk_bf16_f32 v154, v154, v155
	v_cvt_pk_bf16_f32 v155, v148, v149
	ds_bpermute_b32 v152, v248, v152
	ds_bpermute_b32 v153, v248, v153
	ds_bpermute_b32 v154, v248, v154
	ds_bpermute_b32 v155, v248, v155
	s_waitcnt lgkmcnt(0)
	global_store_dwordx4 v[146:147], v[152:155], off offset:256
	s_and_b64 vcc, exec, s[42:43]
	v_mov_b32_e32 v147, v9
	v_mov_b32_e32 v146, v8
	v_mov_b32_e32 v153, v7
	v_mov_b32_e32 v152, v6
	v_mov_b32_e32 v149, v17
	v_mov_b32_e32 v148, v16
	v_mov_b32_e32 v151, v15
	v_mov_b32_e32 v150, v14
	s_cbranch_vccnz .LBB0_352
	v_mul_f32_e32 v147, 0xbfb8aa3b, v6
	v_mul_f32_e32 v149, 0xbfb8aa3b, v8
	v_mul_f32_e32 v146, 0xbfb8aa3b, v14
	v_exp_f32_e32 v152, v147
	v_mul_f32_e32 v147, 0xbfb8aa3b, v15
	v_mul_f32_e32 v150, 0xbfb8aa3b, v7
	v_mul_f32_e32 v148, 0xbfb8aa3b, v16
	v_exp_f32_e32 v154, v149
	v_mul_f32_e32 v149, 0xbfb8aa3b, v17
	v_mul_f32_e32 v151, 0xbfb8aa3b, v9
	v_exp_f32_e32 v146, v146
	v_exp_f32_e32 v147, v147
	v_exp_f32_e32 v148, v148
	v_exp_f32_e32 v149, v149
	v_exp_f32_e32 v155, v151
	v_exp_f32_e32 v153, v150
	v_pk_add_f32 v[150:151], v[146:147], 1.0 op_sel_hi:[1,0]
	v_pk_add_f32 v[148:149], v[148:149], 1.0 op_sel_hi:[1,0]
	v_pk_add_f32 v[146:147], v[154:155], 1.0 op_sel_hi:[1,0]
	v_pk_add_f32 v[152:153], v[152:153], 1.0 op_sel_hi:[1,0]
; __device__ __forceinline__ unsigned cvt_pk_bf16(float lo, float hi) { unsigned r; asm volatile("v_cvt_pk_bf16_f32 %0, %1, %2" : "=v"(r) : "v"(lo), "v"(hi)); return r; }
;     __device__ __forceinline__ void operator()(const f32x4 (&acc)[2][2][4][2], const Unit& u, int wr, int wc, int fr, int fq) const {
;         const int row0 = u.pm * BM + wr * 64 + fr, col0 = u.pn * HALF + wc * 32 + 8 * fq;
; #pragma unroll
;         for (int ai = 0; ai < 2; ++ai)
; #pragma unroll
;             for (int m = 0; m < 4; ++m) {
;                 f32x4 hv[2];
; #pragma unroll
;                 for (int n = 0; n < 2; ++n) {
;                     const f32x4 g = acc[ai][0][m][n], up = acc[ai][1][m][n];
;                     const f32x4 t = g * (-1.44269504088896341f);
;                     f32x4 d; d[0] = __builtin_amdgcn_exp2f(t[0]); d[1] = __builtin_amdgcn_exp2f(t[1]); d[2] = __builtin_amdgcn_exp2f(t[2]); d[3] = __builtin_amdgcn_exp2f(t[3]);
;                     d = d + 1.0f;
;                     f32x4 r; r[0] = __builtin_amdgcn_rcpf(d[0]); r[1] = __builtin_amdgcn_rcpf(d[1]); r[2] = __builtin_amdgcn_rcpf(d[2]); r[3] = __builtin_amdgcn_rcpf(d[3]);
;                     hv[n] = (g * up) * r;
;                 }
;                 u32x4 w; w.x = cvt_pk_bf16(hv[0][0], hv[0][1]); w.y = cvt_pk_bf16(hv[0][2], hv[0][3]); w.z = cvt_pk_bf16(hv[1][0], hv[1][1]); w.w = cvt_pk_bf16(hv[1][2], hv[1][3]);
;                 *(u32x4*)(H + (size_t)(row0 + ai * HALF + m * 16) * ldh + col0) = w;
;     __device__ __forceinline__ void operator()(const f32x4 (&acc)[2][2][4][2], const Unit& u, int wr, int wc, int fr, int fq) const {
;     ...
;             for (int m = 0; m < 4; ++m)
; #pragma unroll
;                 for (int bj = 0; bj < 2; ++bj) {
;                     f32x4 v0 = acc[ai][bj][m][0], v1 = acc[ai][bj][m][1];
;                     if (isg) {
; #pragma unroll
;                         for (int j = 0; j < 4; ++j) { v0[j] = 1.f + __builtin_amdgcn_exp2f(v0[j] * -1.44269504088896341f); v1[j] = 1.f + __builtin_amdgcn_exp2f(v1[j] * -1.44269504088896341f); }
;                     }
;                     u32x4 w; w.x = cvt_pk_bf16(v0[0], v0[1]); w.y = cvt_pk_bf16(v0[2], v0[3]); w.z = cvt_pk_bf16(v1[0], v1[1]); w.w = cvt_pk_bf16(v1[2], v1[3]);
;                     *(u32x4*)(base + (size_t)(row0 + ai * HALF + m * 16) * ld + col0 + bj * HALF) = w;
;                 }
.LBB0_352:
	v_add_u32_e32 v154, 0xb0, v161
	v_mad_i64_i32 v[154:155], s[14:15], s14, v154, 0
	v_lshl_add_u64 v[130:131], v[154:155], 1, v[130:131]
	v_cvt_pk_bf16_f32 v150, v150, v151
	v_cvt_pk_bf16_f32 v151, v148, v149
	v_cvt_pk_bf16_f32 v152, v152, v153
	v_cvt_pk_bf16_f32 v153, v146, v147
	ds_bpermute_b32 v150, v248, v150
	ds_bpermute_b32 v151, v248, v151
	ds_bpermute_b32 v152, v248, v152
	ds_bpermute_b32 v153, v248, v153
	s_waitcnt lgkmcnt(0)
	global_store_dwordx4 v[130:131], v[150:153], off
	s_and_b64 vcc, exec, s[42:43]
	v_mov_b32_e32 v147, v5
	v_mov_b32_e32 v146, v4
	v_mov_b32_e32 v151, v3
	v_mov_b32_e32 v150, v2
	v_mov_b32_e32 v149, v13
	v_mov_b32_e32 v148, v12
	v_mov_b32_e32 v153, v11
	v_mov_b32_e32 v152, v10
	s_cbranch_vccnz .LBB0_354
	v_mul_f32_e32 v147, 0xbfb8aa3b, v2
	v_mul_f32_e32 v149, 0xbfb8aa3b, v4
	v_mul_f32_e32 v146, 0xbfb8aa3b, v10
	v_exp_f32_e32 v150, v147
	v_mul_f32_e32 v147, 0xbfb8aa3b, v11
	v_mul_f32_e32 v151, 0xbfb8aa3b, v3
	v_mul_f32_e32 v148, 0xbfb8aa3b, v12
	v_exp_f32_e32 v154, v149
	v_mul_f32_e32 v149, 0xbfb8aa3b, v13
	v_mul_f32_e32 v152, 0xbfb8aa3b, v5
	v_exp_f32_e32 v146, v146
	v_exp_f32_e32 v147, v147
	v_exp_f32_e32 v148, v148
	v_exp_f32_e32 v149, v149
	v_exp_f32_e32 v155, v152
	v_exp_f32_e32 v151, v151
	v_pk_add_f32 v[152:153], v[146:147], 1.0 op_sel_hi:[1,0]
	v_pk_add_f32 v[148:149], v[148:149], 1.0 op_sel_hi:[1,0]
	v_pk_add_f32 v[146:147], v[154:155], 1.0 op_sel_hi:[1,0]
	v_pk_add_f32 v[150:151], v[150:151], 1.0 op_sel_hi:[1,0]
.LBB0_354:
	v_cvt_pk_bf16_f32 v152, v152, v153
	v_cvt_pk_bf16_f32 v153, v148, v149
	s_nop 0
	v_cvt_pk_bf16_f32 v154, v150, v151
	v_cvt_pk_bf16_f32 v155, v146, v147
	ds_bpermute_b32 v152, v248, v152
	ds_bpermute_b32 v153, v248, v153
	ds_bpermute_b32 v154, v248, v154
	ds_bpermute_b32 v155, v248, v155
	s_waitcnt lgkmcnt(0)
	global_store_dwordx4 v[130:131], v[152:155], off offset:256
	s_branch .LBB0_356
.LBB0_355:
	v_readfirstlane_b32 s14, v133
	v_readfirstlane_b32 s15, v132
	v_pk_mul_f32 v[148:149], v[126:127], s[36:37] op_sel_hi:[1,0]
	v_mov_b32_e32 v131, s14
	v_mov_b32_e32 v130, s15
	s_lshl_b32 s14, s54, 8
	s_lshl_b32 s15, s55, 6
	s_add_i32 s15, s15, s14
	v_add_u32_e32 v132, s15, v160
	s_lshl_b32 s14, s53, 7
	s_lshl_b32 s15, s34, 5
	s_add_i32 s15, s15, s14
	v_lshl_add_u32 v146, v159, 3, s15
	v_ashrrev_i32_e32 v147, 31, v146
	v_lshl_add_u64 v[130:131], v[146:147], 1, v[130:131]
	v_pk_mul_f32 v[146:147], v[128:129], s[36:37] op_sel_hi:[1,0]
	v_pk_mul_f32 v[124:125], v[128:129], v[124:125]
	v_pk_mul_f32 v[122:123], v[126:127], v[122:123]
	v_pk_mul_f32 v[126:127], v[120:121], s[36:37] op_sel_hi:[1,0]
	v_pk_mul_f32 v[128:129], v[118:119], s[36:37] op_sel_hi:[1,0]
	v_exp_f32_e32 v126, v126
	v_exp_f32_e32 v128, v128
	v_exp_f32_e32 v129, v129
	v_exp_f32_e32 v127, v127
	v_exp_f32_e32 v148, v148
	v_exp_f32_e32 v149, v149
	v_exp_f32_e32 v146, v146
	v_exp_f32_e32 v147, v147
	v_pk_add_f32 v[126:127], v[126:127], 1.0 op_sel_hi:[1,0]
	v_pk_add_f32 v[128:129], v[128:129], 1.0 op_sel_hi:[1,0]
	v_pk_add_f32 v[148:149], v[148:149], 1.0 op_sel_hi:[1,0]
	v_pk_add_f32 v[146:147], v[146:147], 1.0 op_sel_hi:[1,0]
	v_rcp_f32_e32 v128, v128
	v_rcp_f32_e32 v129, v129
	v_rcp_f32_e32 v126, v126
	v_rcp_f32_e32 v127, v127
	v_rcp_f32_e32 v148, v148
	v_rcp_f32_e32 v149, v149
	v_rcp_f32_e32 v146, v146
	v_rcp_f32_e32 v147, v147
	v_pk_mul_f32 v[116:117], v[120:121], v[116:117]
	v_pk_mul_f32 v[114:115], v[118:119], v[114:115]
	v_pk_mul_f32 v[118:119], v[126:127], v[116:117]
	v_pk_mul_f32 v[116:117], v[128:129], v[114:115]
	s_movk_i32 s34, 0x1600
	v_pk_mul_f32 v[124:125], v[146:147], v[124:125]
	v_pk_mul_f32 v[122:123], v[148:149], v[122:123]
	v_pk_mul_f32 v[108:109], v[112:113], v[108:109]
	v_cvt_pk_bf16_f32 v114, v122, v123
	v_cvt_pk_bf16_f32 v115, v124, v125
	v_cvt_pk_bf16_f32 v116, v116, v117
	v_cvt_pk_bf16_f32 v117, v118, v119
	v_mad_i64_i32 v[118:119], s[14:15], v132, s34, v[130:131]
	ds_bpermute_b32 v114, v248, v114
	ds_bpermute_b32 v115, v248, v115
	ds_bpermute_b32 v116, v248, v116
	ds_bpermute_b32 v117, v248, v117
	s_waitcnt lgkmcnt(0)
	global_store_dwordx4 v[118:119], v[114:117], off
	v_pk_mul_f32 v[106:107], v[110:111], v[106:107]
	v_pk_mul_f32 v[100:101], v[104:105], v[100:101]
	v_pk_mul_f32 v[114:115], v[112:113], s[36:37] op_sel_hi:[1,0]
	v_pk_mul_f32 v[116:117], v[110:111], s[36:37] op_sel_hi:[1,0]
	v_pk_mul_f32 v[110:111], v[104:105], s[36:37] op_sel_hi:[1,0]
	v_pk_mul_f32 v[112:113], v[102:103], s[36:37] op_sel_hi:[1,0]
	v_exp_f32_e32 v110, v110
	v_exp_f32_e32 v112, v112
	v_exp_f32_e32 v113, v113
	v_exp_f32_e32 v111, v111
	v_exp_f32_e32 v116, v116
	v_exp_f32_e32 v117, v117
	v_exp_f32_e32 v114, v114
	v_exp_f32_e32 v115, v115
	v_pk_add_f32 v[110:111], v[110:111], 1.0 op_sel_hi:[1,0]
	v_pk_add_f32 v[112:113], v[112:113], 1.0 op_sel_hi:[1,0]
	v_pk_add_f32 v[116:117], v[116:117], 1.0 op_sel_hi:[1,0]
	v_pk_add_f32 v[114:115], v[114:115], 1.0 op_sel_hi:[1,0]
	v_rcp_f32_e32 v112, v112
	v_rcp_f32_e32 v113, v113
	v_rcp_f32_e32 v110, v110
	v_rcp_f32_e32 v111, v111
	v_rcp_f32_e32 v116, v116
	v_rcp_f32_e32 v117, v117
	v_rcp_f32_e32 v114, v114
	v_rcp_f32_e32 v115, v115
	v_pk_mul_f32 v[98:99], v[102:103], v[98:99]
	v_pk_mul_f32 v[102:103], v[110:111], v[100:101]
	v_pk_mul_f32 v[100:101], v[112:113], v[98:99]
	v_pk_mul_f32 v[108:109], v[114:115], v[108:109]
	v_pk_mul_f32 v[106:107], v[116:117], v[106:107]
	v_pk_mul_f32 v[92:93], v[96:97], v[92:93]
	v_cvt_pk_bf16_f32 v98, v106, v107
	v_cvt_pk_bf16_f32 v99, v108, v109
	v_cvt_pk_bf16_f32 v100, v100, v101
	v_cvt_pk_bf16_f32 v101, v102, v103
	v_add_u32_e32 v102, 16, v132
	v_mad_i64_i32 v[102:103], s[14:15], v102, s34, v[130:131]
	ds_bpermute_b32 v98, v248, v98
	ds_bpermute_b32 v99, v248, v99
	ds_bpermute_b32 v100, v248, v100
	ds_bpermute_b32 v101, v248, v101
	s_waitcnt lgkmcnt(0)
; __device__ __forceinline__ unsigned cvt_pk_bf16(float lo, float hi) { unsigned r; asm volatile("v_cvt_pk_bf16_f32 %0, %1, %2" : "=v"(r) : "v"(lo), "v"(hi)); return r; }
;     __device__ __forceinline__ void operator()(const f32x4 (&acc)[2][2][4][2], const Unit& u, int wr, int wc, int fr, int fq) const {
;     ...
; #pragma unroll
;         for (int ai = 0; ai < 2; ++ai)
; #pragma unroll
;             for (int m = 0; m < 4; ++m) {
;                 f32x4 hv[2];
; #pragma unroll
;                 for (int n = 0; n < 2; ++n) {
;                     const f32x4 g = acc[ai][0][m][n], up = acc[ai][1][m][n];
;                     const f32x4 t = g * (-1.44269504088896341f);
;                     f32x4 d; d[0] = __builtin_amdgcn_exp2f(t[0]); d[1] = __builtin_amdgcn_exp2f(t[1]); d[2] = __builtin_amdgcn_exp2f(t[2]); d[3] = __builtin_amdgcn_exp2f(t[3]);
;                     d = d + 1.0f;
;                     f32x4 r; r[0] = __builtin_amdgcn_rcpf(d[0]); r[1] = __builtin_amdgcn_rcpf(d[1]); r[2] = __builtin_amdgcn_rcpf(d[2]); r[3] = __builtin_amdgcn_rcpf(d[3]);
;                     hv[n] = (g * up) * r;
;                 }
;                 u32x4 w; w.x = cvt_pk_bf16(hv[0][0], hv[0][1]); w.y = cvt_pk_bf16(hv[0][2], hv[0][3]); w.z = cvt_pk_bf16(hv[1][0], hv[1][1]); w.w = cvt_pk_bf16(hv[1][2], hv[1][3]);
;                 *(u32x4*)(H + (size_t)(row0 + ai * HALF + m * 16) * ldh + col0) = w;
	global_store_dwordx4 v[102:103], v[98:101], off
	v_pk_mul_f32 v[90:91], v[94:95], v[90:91]
	v_pk_mul_f32 v[84:85], v[88:89], v[84:85]
	v_pk_mul_f32 v[98:99], v[96:97], s[36:37] op_sel_hi:[1,0]
	v_pk_mul_f32 v[100:101], v[94:95], s[36:37] op_sel_hi:[1,0]
	v_pk_mul_f32 v[94:95], v[88:89], s[36:37] op_sel_hi:[1,0]
	v_pk_mul_f32 v[96:97], v[86:87], s[36:37] op_sel_hi:[1,0]
	v_exp_f32_e32 v94, v94
	v_exp_f32_e32 v96, v96
	v_exp_f32_e32 v97, v97
	v_exp_f32_e32 v95, v95
	v_exp_f32_e32 v100, v100
	v_exp_f32_e32 v101, v101
	v_exp_f32_e32 v98, v98
	v_exp_f32_e32 v99, v99
	v_pk_add_f32 v[94:95], v[94:95], 1.0 op_sel_hi:[1,0]
	v_pk_add_f32 v[96:97], v[96:97], 1.0 op_sel_hi:[1,0]
	v_pk_add_f32 v[100:101], v[100:101], 1.0 op_sel_hi:[1,0]
	v_pk_add_f32 v[98:99], v[98:99], 1.0 op_sel_hi:[1,0]
	v_rcp_f32_e32 v96, v96
	v_rcp_f32_e32 v97, v97
	v_rcp_f32_e32 v94, v94
	v_rcp_f32_e32 v95, v95
	v_rcp_f32_e32 v100, v100
	v_rcp_f32_e32 v101, v101
	v_rcp_f32_e32 v98, v98
	v_rcp_f32_e32 v99, v99
	v_pk_mul_f32 v[82:83], v[86:87], v[82:83]
	v_pk_mul_f32 v[86:87], v[94:95], v[84:85]
	v_pk_mul_f32 v[84:85], v[96:97], v[82:83]
	v_pk_mul_f32 v[92:93], v[98:99], v[92:93]
	v_pk_mul_f32 v[90:91], v[100:101], v[90:91]
	v_pk_mul_f32 v[76:77], v[80:81], v[76:77]
	v_cvt_pk_bf16_f32 v82, v90, v91
	v_cvt_pk_bf16_f32 v83, v92, v93
	v_cvt_pk_bf16_f32 v84, v84, v85
	v_cvt_pk_bf16_f32 v85, v86, v87
	v_add_u32_e32 v86, 32, v132
	v_mad_i64_i32 v[86:87], s[14:15], v86, s34, v[130:131]
	ds_bpermute_b32 v82, v248, v82
	ds_bpermute_b32 v83, v248, v83
	ds_bpermute_b32 v84, v248, v84
	ds_bpermute_b32 v85, v248, v85
	s_waitcnt lgkmcnt(0)
	global_store_dwordx4 v[86:87], v[82:85], off
	v_pk_mul_f32 v[74:75], v[78:79], v[74:75]
	v_pk_mul_f32 v[68:69], v[72:73], v[68:69]
	v_pk_mul_f32 v[82:83], v[80:81], s[36:37] op_sel_hi:[1,0]
	v_pk_mul_f32 v[84:85], v[78:79], s[36:37] op_sel_hi:[1,0]
	v_pk_mul_f32 v[78:79], v[72:73], s[36:37] op_sel_hi:[1,0]
	v_pk_mul_f32 v[80:81], v[70:71], s[36:37] op_sel_hi:[1,0]
	v_exp_f32_e32 v78, v78
	v_exp_f32_e32 v80, v80
	v_exp_f32_e32 v81, v81
	v_exp_f32_e32 v79, v79
	v_exp_f32_e32 v84, v84
	v_exp_f32_e32 v85, v85
	v_exp_f32_e32 v82, v82
	v_exp_f32_e32 v83, v83
	v_pk_add_f32 v[78:79], v[78:79], 1.0 op_sel_hi:[1,0]
	v_pk_add_f32 v[80:81], v[80:81], 1.0 op_sel_hi:[1,0]
	v_pk_add_f32 v[84:85], v[84:85], 1.0 op_sel_hi:[1,0]
	v_pk_add_f32 v[82:83], v[82:83], 1.0 op_sel_hi:[1,0]
	v_rcp_f32_e32 v80, v80
	v_rcp_f32_e32 v81, v81
	v_rcp_f32_e32 v78, v78
	v_rcp_f32_e32 v79, v79
	v_rcp_f32_e32 v84, v84
	v_rcp_f32_e32 v85, v85
	v_rcp_f32_e32 v82, v82
	v_rcp_f32_e32 v83, v83
	v_pk_mul_f32 v[66:67], v[70:71], v[66:67]
	v_pk_mul_f32 v[70:71], v[78:79], v[68:69]
	v_pk_mul_f32 v[68:69], v[80:81], v[66:67]
	v_pk_mul_f32 v[76:77], v[82:83], v[76:77]
	v_pk_mul_f32 v[74:75], v[84:85], v[74:75]
	v_pk_mul_f32 v[60:61], v[64:65], v[60:61]
	v_cvt_pk_bf16_f32 v66, v74, v75
	v_cvt_pk_bf16_f32 v67, v76, v77
	v_cvt_pk_bf16_f32 v68, v68, v69
	v_cvt_pk_bf16_f32 v69, v70, v71
	v_add_u32_e32 v70, 48, v132
	v_mad_i64_i32 v[70:71], s[14:15], v70, s34, v[130:131]
	ds_bpermute_b32 v66, v248, v66
	ds_bpermute_b32 v67, v248, v67
	ds_bpermute_b32 v68, v248, v68
	ds_bpermute_b32 v69, v248, v69
	s_waitcnt lgkmcnt(0)
	global_store_dwordx4 v[70:71], v[66:69], off
	v_pk_mul_f32 v[58:59], v[62:63], v[58:59]
	v_pk_mul_f32 v[52:53], v[56:57], v[52:53]
	v_pk_mul_f32 v[66:67], v[64:65], s[36:37] op_sel_hi:[1,0]
	v_pk_mul_f32 v[68:69], v[62:63], s[36:37] op_sel_hi:[1,0]
	v_pk_mul_f32 v[62:63], v[56:57], s[36:37] op_sel_hi:[1,0]
	v_pk_mul_f32 v[64:65], v[54:55], s[36:37] op_sel_hi:[1,0]
	v_exp_f32_e32 v62, v62
	v_exp_f32_e32 v64, v64
	v_exp_f32_e32 v65, v65
	v_exp_f32_e32 v63, v63
	v_exp_f32_e32 v68, v68
	v_exp_f32_e32 v69, v69
	v_exp_f32_e32 v66, v66
	v_exp_f32_e32 v67, v67
	v_pk_add_f32 v[62:63], v[62:63], 1.0 op_sel_hi:[1,0]
	v_pk_add_f32 v[64:65], v[64:65], 1.0 op_sel_hi:[1,0]
	v_pk_add_f32 v[68:69], v[68:69], 1.0 op_sel_hi:[1,0]
	v_pk_add_f32 v[66:67], v[66:67], 1.0 op_sel_hi:[1,0]
	v_rcp_f32_e32 v64, v64
	v_rcp_f32_e32 v65, v65
	v_rcp_f32_e32 v62, v62
	v_rcp_f32_e32 v63, v63
	v_rcp_f32_e32 v68, v68
	v_rcp_f32_e32 v69, v69
	v_rcp_f32_e32 v66, v66
	v_rcp_f32_e32 v67, v67
	v_pk_mul_f32 v[50:51], v[54:55], v[50:51]
	v_add_u32_e32 v70, 0x80, v132
	v_pk_mul_f32 v[54:55], v[62:63], v[52:53]
	v_pk_mul_f32 v[52:53], v[64:65], v[50:51]
	v_pk_mul_f32 v[60:61], v[66:67], v[60:61]
	v_pk_mul_f32 v[58:59], v[68:69], v[58:59]
	v_pk_mul_f32 v[44:45], v[48:49], v[44:45]
	v_cvt_pk_bf16_f32 v50, v58, v59
	v_cvt_pk_bf16_f32 v51, v60, v61
	v_cvt_pk_bf16_f32 v52, v52, v53
	v_cvt_pk_bf16_f32 v53, v54, v55
	v_mad_i64_i32 v[54:55], s[14:15], v70, s34, v[130:131]
	ds_bpermute_b32 v50, v248, v50
	ds_bpermute_b32 v51, v248, v51
	ds_bpermute_b32 v52, v248, v52
	ds_bpermute_b32 v53, v248, v53
	s_waitcnt lgkmcnt(0)
; __device__ __forceinline__ unsigned cvt_pk_bf16(float lo, float hi) { unsigned r; asm volatile("v_cvt_pk_bf16_f32 %0, %1, %2" : "=v"(r) : "v"(lo), "v"(hi)); return r; }
;     __device__ __forceinline__ void operator()(const f32x4 (&acc)[2][2][4][2], const Unit& u, int wr, int wc, int fr, int fq) const {
;     ...
; #pragma unroll
;         for (int ai = 0; ai < 2; ++ai)
; #pragma unroll
;             for (int m = 0; m < 4; ++m) {
;                 f32x4 hv[2];
; #pragma unroll
;                 for (int n = 0; n < 2; ++n) {
;                     const f32x4 g = acc[ai][0][m][n], up = acc[ai][1][m][n];
;                     const f32x4 t = g * (-1.44269504088896341f);
;                     f32x4 d; d[0] = __builtin_amdgcn_exp2f(t[0]); d[1] = __builtin_amdgcn_exp2f(t[1]); d[2] = __builtin_amdgcn_exp2f(t[2]); d[3] = __builtin_amdgcn_exp2f(t[3]);
;                     d = d + 1.0f;
;                     f32x4 r; r[0] = __builtin_amdgcn_rcpf(d[0]); r[1] = __builtin_amdgcn_rcpf(d[1]); r[2] = __builtin_amdgcn_rcpf(d[2]); r[3] = __builtin_amdgcn_rcpf(d[3]);
;                     hv[n] = (g * up) * r;
;                 }
;                 u32x4 w; w.x = cvt_pk_bf16(hv[0][0], hv[0][1]); w.y = cvt_pk_bf16(hv[0][2], hv[0][3]); w.z = cvt_pk_bf16(hv[1][0], hv[1][1]); w.w = cvt_pk_bf16(hv[1][2], hv[1][3]);
;                 *(u32x4*)(H + (size_t)(row0 + ai * HALF + m * 16) * ldh + col0) = w;
	global_store_dwordx4 v[54:55], v[50:53], off
	v_pk_mul_f32 v[42:43], v[46:47], v[42:43]
	v_pk_mul_f32 v[36:37], v[40:41], v[36:37]
	v_pk_mul_f32 v[50:51], v[48:49], s[36:37] op_sel_hi:[1,0]
	v_pk_mul_f32 v[52:53], v[46:47], s[36:37] op_sel_hi:[1,0]
	v_pk_mul_f32 v[46:47], v[40:41], s[36:37] op_sel_hi:[1,0]
	v_pk_mul_f32 v[48:49], v[38:39], s[36:37] op_sel_hi:[1,0]
	v_exp_f32_e32 v46, v46
	v_exp_f32_e32 v48, v48
	v_exp_f32_e32 v49, v49
	v_exp_f32_e32 v47, v47
	v_exp_f32_e32 v52, v52
	v_exp_f32_e32 v53, v53
	v_exp_f32_e32 v50, v50
	v_exp_f32_e32 v51, v51
	v_pk_add_f32 v[46:47], v[46:47], 1.0 op_sel_hi:[1,0]
	v_pk_add_f32 v[48:49], v[48:49], 1.0 op_sel_hi:[1,0]
	v_pk_add_f32 v[52:53], v[52:53], 1.0 op_sel_hi:[1,0]
	v_pk_add_f32 v[50:51], v[50:51], 1.0 op_sel_hi:[1,0]
	v_rcp_f32_e32 v48, v48
	v_rcp_f32_e32 v49, v49
	v_rcp_f32_e32 v46, v46
	v_rcp_f32_e32 v47, v47
	v_rcp_f32_e32 v52, v52
	v_rcp_f32_e32 v53, v53
	v_rcp_f32_e32 v50, v50
	v_rcp_f32_e32 v51, v51
	v_pk_mul_f32 v[34:35], v[38:39], v[34:35]
	v_pk_mul_f32 v[38:39], v[46:47], v[36:37]
	v_pk_mul_f32 v[36:37], v[48:49], v[34:35]
	v_pk_mul_f32 v[44:45], v[50:51], v[44:45]
	v_pk_mul_f32 v[42:43], v[52:53], v[42:43]
	v_pk_mul_f32 v[28:29], v[32:33], v[28:29]
	v_cvt_pk_bf16_f32 v34, v42, v43
	v_cvt_pk_bf16_f32 v35, v44, v45
	v_cvt_pk_bf16_f32 v36, v36, v37
	v_cvt_pk_bf16_f32 v37, v38, v39
	v_add_u32_e32 v38, 0x90, v132
	v_mad_i64_i32 v[38:39], s[14:15], v38, s34, v[130:131]
	ds_bpermute_b32 v34, v248, v34
	ds_bpermute_b32 v35, v248, v35
	ds_bpermute_b32 v36, v248, v36
	ds_bpermute_b32 v37, v248, v37
	s_waitcnt lgkmcnt(0)
	global_store_dwordx4 v[38:39], v[34:37], off
	v_pk_mul_f32 v[26:27], v[30:31], v[26:27]
	v_pk_mul_f32 v[20:21], v[24:25], v[20:21]
	v_pk_mul_f32 v[34:35], v[32:33], s[36:37] op_sel_hi:[1,0]
	v_pk_mul_f32 v[36:37], v[30:31], s[36:37] op_sel_hi:[1,0]
	v_pk_mul_f32 v[30:31], v[24:25], s[36:37] op_sel_hi:[1,0]
	v_pk_mul_f32 v[32:33], v[22:23], s[36:37] op_sel_hi:[1,0]
	v_exp_f32_e32 v30, v30
	v_exp_f32_e32 v32, v32
	v_exp_f32_e32 v33, v33
	v_exp_f32_e32 v31, v31
	v_exp_f32_e32 v36, v36
	v_exp_f32_e32 v37, v37
	v_exp_f32_e32 v34, v34
	v_exp_f32_e32 v35, v35
	v_pk_add_f32 v[30:31], v[30:31], 1.0 op_sel_hi:[1,0]
	v_pk_add_f32 v[32:33], v[32:33], 1.0 op_sel_hi:[1,0]
	v_pk_add_f32 v[36:37], v[36:37], 1.0 op_sel_hi:[1,0]
	v_pk_add_f32 v[34:35], v[34:35], 1.0 op_sel_hi:[1,0]
	v_rcp_f32_e32 v32, v32
	v_rcp_f32_e32 v33, v33
	v_rcp_f32_e32 v30, v30
	v_rcp_f32_e32 v31, v31
	v_rcp_f32_e32 v36, v36
	v_rcp_f32_e32 v37, v37
	v_rcp_f32_e32 v34, v34
	v_rcp_f32_e32 v35, v35
	v_pk_mul_f32 v[18:19], v[22:23], v[18:19]
	v_pk_mul_f32 v[22:23], v[30:31], v[20:21]
	v_pk_mul_f32 v[20:21], v[32:33], v[18:19]
	v_pk_mul_f32 v[28:29], v[34:35], v[28:29]
	v_pk_mul_f32 v[26:27], v[36:37], v[26:27]
	v_pk_mul_f32 v[12:13], v[16:17], v[12:13]
	v_cvt_pk_bf16_f32 v18, v26, v27
	v_cvt_pk_bf16_f32 v19, v28, v29
	v_cvt_pk_bf16_f32 v20, v20, v21
	v_cvt_pk_bf16_f32 v21, v22, v23
	v_add_u32_e32 v22, 0xa0, v132
	v_mad_i64_i32 v[22:23], s[14:15], v22, s34, v[130:131]
	ds_bpermute_b32 v18, v248, v18
	ds_bpermute_b32 v19, v248, v19
	ds_bpermute_b32 v20, v248, v20
	ds_bpermute_b32 v21, v248, v21
	s_waitcnt lgkmcnt(0)
	global_store_dwordx4 v[22:23], v[18:21], off
	v_pk_mul_f32 v[10:11], v[14:15], v[10:11]
	v_pk_mul_f32 v[4:5], v[8:9], v[4:5]
	v_pk_mul_f32 v[18:19], v[16:17], s[36:37] op_sel_hi:[1,0]
	v_pk_mul_f32 v[20:21], v[14:15], s[36:37] op_sel_hi:[1,0]
	v_pk_mul_f32 v[14:15], v[8:9], s[36:37] op_sel_hi:[1,0]
	v_pk_mul_f32 v[16:17], v[6:7], s[36:37] op_sel_hi:[1,0]
	v_exp_f32_e32 v14, v14
	v_exp_f32_e32 v16, v16
	v_exp_f32_e32 v17, v17
	v_exp_f32_e32 v15, v15
	v_exp_f32_e32 v20, v20
	v_exp_f32_e32 v21, v21
	v_exp_f32_e32 v18, v18
	v_exp_f32_e32 v19, v19
	v_pk_add_f32 v[14:15], v[14:15], 1.0 op_sel_hi:[1,0]
	v_pk_add_f32 v[16:17], v[16:17], 1.0 op_sel_hi:[1,0]
	v_pk_add_f32 v[20:21], v[20:21], 1.0 op_sel_hi:[1,0]
	v_pk_add_f32 v[18:19], v[18:19], 1.0 op_sel_hi:[1,0]
	v_rcp_f32_e32 v16, v16
	v_rcp_f32_e32 v17, v17
	v_rcp_f32_e32 v14, v14
	v_rcp_f32_e32 v15, v15
	v_rcp_f32_e32 v20, v20
	v_rcp_f32_e32 v21, v21
	v_rcp_f32_e32 v18, v18
	v_rcp_f32_e32 v19, v19
	v_pk_mul_f32 v[2:3], v[6:7], v[2:3]
	v_pk_mul_f32 v[6:7], v[14:15], v[4:5]
	v_pk_mul_f32 v[4:5], v[16:17], v[2:3]
	v_pk_mul_f32 v[12:13], v[18:19], v[12:13]
	v_pk_mul_f32 v[10:11], v[20:21], v[10:11]
	s_nop 0
	v_cvt_pk_bf16_f32 v2, v10, v11
	v_cvt_pk_bf16_f32 v3, v12, v13
	v_cvt_pk_bf16_f32 v4, v4, v5
	v_cvt_pk_bf16_f32 v5, v6, v7
	v_add_u32_e32 v6, 0xb0, v132
	v_mad_i64_i32 v[6:7], s[14:15], v6, s34, v[130:131]
	ds_bpermute_b32 v2, v248, v2
	ds_bpermute_b32 v3, v248, v3
	ds_bpermute_b32 v4, v248, v4
	ds_bpermute_b32 v5, v248, v5
	s_waitcnt lgkmcnt(0)
	global_store_dwordx4 v[6:7], v[2:5], off
